# leader invalidate issued right after its cross-XCD arrival; local release issued as soon as the global release is seen, without waiting on the invalidate
# speedup vs baseline: 1.0024x; 1.0024x over previous
; __device__ __forceinline__ unsigned xb_ld(unsigned* p)              { return __hip_atomic_load(p, __ATOMIC_RELAXED, __HIP_MEMORY_SCOPE_AGENT); }
; __device__ __forceinline__ unsigned xb_add(unsigned* p, unsigned v) { return __hip_atomic_fetch_add(p, v, __ATOMIC_RELAXED, __HIP_MEMORY_SCOPE_AGENT); }
; #define XB_SPIN(cond, bar) do { unsigned _sp = 0; while (cond) { __builtin_amdgcn_s_sleep(1); \
;     if ((++_sp & 255u) == 0u) { if (xb_ld(&(bar)[XB_TMO])) break; if (_sp > XB_SPIN_CAP) { atomicAdd(&(bar)[XB_TMO], 1u); break; } } } } while (0)
; __device__ __forceinline__ void xcd_barrier(const XcdBarrier& b) {
;     ...
;         const unsigned old = xb_add(&bar[XB_XSUB(b.x)], 1u);
;         const unsigned gen = old / nloc;
;         if (old + 1u == (gen + 1u) * nloc) {
;             __builtin_amdgcn_fence(__ATOMIC_RELEASE, "agent");
;             asm volatile("s_waitcnt vmcnt(0)" ::: "memory");
;             const unsigned og = xb_add(&bar[XB_TOP], 1u);
;             const unsigned tg = og / nx;
;             if (og + 1u == (tg + 1u) * nx) xb_add(&bar[XB_TOPGEN], 1u);
;             else XB_SPIN(xb_ld(&bar[XB_TOPGEN]) == tg, bar);
;             __builtin_amdgcn_fence(__ATOMIC_ACQUIRE, "agent");
;             xb_add(&bar[XB_XGEN(b.x)], 1u);
;             asm volatile("s_waitcnt vmcnt(0)" ::: "memory");
.LBB0_14:
	s_or_b64 exec, exec, s[8:9]
	v_mov_b32_e32 v0, 0x2000
	global_atomic_add v0, v183, s[6:7] offset:1024
